# last layer panel sync instead of two grid barriers; guard = per-group XCC-id mask (all four workgroups of a row panel on one XCC), checked after phase 1, fallback = grid barrier
# speedup vs baseline: 1.0095x; 1.0030x over previous
_Z10hybrid_fwd4Args:
	s_mov_b32 s3, 0
	v_writelane_b32 v255, s3, 61
	s_mov_b32 s3, 0
	v_writelane_b32 v255, s3, 62
	s_load_dwordx4 s[52:55], s[0:1], 0x90
	s_mov_b32 s78, s2
	s_add_u32 s2, s0, 0xa0
	v_writelane_b32 v252, s0, 0
	s_addc_u32 s3, s1, 0
	v_and_b32_e32 v191, 0x3ff, v0
	v_writelane_b32 v252, s1, 1
	v_writelane_b32 v252, s2, 2
	v_cmp_gt_u32_e32 vcc, 64, v191
	s_nop 0
	v_writelane_b32 v252, s3, 3
	s_and_saveexec_b64 s[0:1], vcc
	v_lshl_add_u32 v1, v191, 2, 0
	v_add_u32_e32 v1, 0x24000, v1
	v_mov_b32_e32 v2, 0
	ds_write_b32 v1, v2
	s_or_b64 exec, exec, s[0:1]
	v_readlane_b32 s0, v252, 0
	v_readlane_b32 s1, v252, 1
	s_load_dwordx2 s[80:81], s[0:1], 0xa0
	s_waitcnt lgkmcnt(0)
	s_barrier
	s_getreg_b32 s0, hwreg(HW_REG_XCC_ID, 0, 4)
	s_and_b32 s4, s0, 15
	v_cmp_eq_u32_e64 s[2:3], 0, v191
	s_mov_b64 s[0:1], exec
	s_nop 0
	v_writelane_b32 v252, s2, 4
	s_nop 1
	v_writelane_b32 v252, s3, 5
	s_and_b64 s[2:3], s[0:1], s[2:3]
	s_mov_b64 exec, s[2:3]
	s_cbranch_execz .LBB0_5
	s_mov_b64 s[2:3], exec
	v_mbcnt_lo_u32_b32 v1, s2, 0
	v_mbcnt_hi_u32_b32 v1, s3, v1
	v_cmp_eq_u32_e32 vcc, 0, v1
	s_and_b64 s[6:7], exec, vcc
	s_mov_b64 exec, s[6:7]
	s_cbranch_execz .LBB0_5
	s_lshl_b32 s5, s4, 8
	s_bcnt1_i32_b64 s2, s[2:3]
	v_mov_b32_e32 v1, s5
	v_mov_b32_e32 v2, s2
	global_atomic_add v1, v2, s[52:53] offset:1024
	s_and_b32 s5, s78, 7
	s_lshl_b32 s5, s5, 3
	s_bfe_u32 s6, s78, 0x30003
	s_or_b32 s5, s5, s6
	s_lshl_b32 s5, s5, 2
	s_add_i32 s5, s5, 0x17800
	s_lshl_b32 s6, 1, s4
	v_mov_b32_e32 v1, s5
	v_mov_b32_e32 v2, s6
	s_nop 0
	global_atomic_or v1, v2, s[52:53]

.LBB0_1378:
	s_cmp_eq_u32 s54, 1
	s_cbranch_scc0 .Lgm_done
	v_readlane_b32 s0, v254, 10
	v_readlane_b32 s1, v254, 11
	s_nop 3
	s_and_b32 s2, s78, 7
	s_lshl_b32 s2, s2, 3
	s_bfe_u32 s3, s78, 0x30003
	s_or_b32 s2, s2, s3
	s_lshl_b32 s2, s2, 2
	s_add_i32 s2, s2, 0x17800
	s_add_u32 s2, s0, s2
	s_addc_u32 s3, s1, 0
	s_mov_b64 vcc, exec
	s_mov_b32 exec_lo, 0
	s_brev_b32 exec_hi, 1
	global_load_dword v255, v1, s[2:3] sc1
	s_waitcnt vmcnt(0)
	v_readlane_b32 s2, v255, 63
	s_nop 3
	s_bcnt1_i32_b32 s2, s2
	s_cmp_eq_u32 s2, 1
	s_cbranch_scc1 .Lgm_ok
	v_readfirstlane_b32 s2, v191
	s_nop 3
	s_cmp_lt_u32 s2, 64
	s_cbranch_scc0 .Lgm_ok
	s_add_u32 s0, s0, 0x16e00
	s_addc_u32 s1, s1, 0
	global_atomic_add v1, v220, s[0:1]
.Lgm_ok:
	s_mov_b64 exec, vcc
